# P5 sab-load batching + token-MLP ds_read pipelining, all later code kept at baseline+4 byte placement (91 pad nops in dead code + 1 early)
# speedup vs baseline: 1.0147x; 1.0147x over previous
; #define LAS __attribute__((address_space(3)))
; __global__ void __launch_bounds__(NTHREADS, 2) mega(Args a) {
;     extern __shared__ __attribute__((aligned(16))) unsigned char lds_raw[];
;     ...
;     cg::grid_group grid = cg::this_grid();
;     volatile LAS unsigned* bst = (volatile LAS unsigned*)((LAS unsigned char*)lds_raw + 131072);
;     if (threadIdx.x < 4) bst[threadIdx.x] = 0u;
;     __syncthreads();
;     XcdBarrier xbar = xcd_barrier_post((unsigned*)(a.ws + WS_BAR), bst);
;     int ph = 0;
;     ...
;     if (RUN(ph)) { MKCTX();
.LBB0_103:
	s_mul_i32 s2, s75, s74
	s_ashr_i32 s75, s74, 31
	s_cmp_gt_i32 s73, -1
	s_cselect_b64 s[4:5], -1, 0
	v_writelane_b32 v250, s4, 11
	s_mul_i32 s2, s2, s46
	v_lshrrev_b32_e32 v1, 20, v0
	v_writelane_b32 v250, s5, 12
	v_writelane_b32 v250, s2, 13
	s_add_u32 s2, s70, 0x5da0200
	s_addc_u32 s3, s71, 0
	v_writelane_b32 v250, s2, 14
	v_lshrrev_b32_e32 v0, 10, v0
	v_or_b32_e32 v0, v0, v1
	v_writelane_b32 v250, s3, 15
	s_add_u32 s2, s70, 0x5da0400
	s_addc_u32 s3, s71, 0
	v_writelane_b32 v250, s2, 16
	s_mov_b32 s39, 0
	v_mov_b32_e32 v223, 0x358637bd
	v_writelane_b32 v250, s3, 17
	s_add_u32 s2, s70, 0x5da0500
	s_addc_u32 s3, s71, 0
	v_writelane_b32 v250, s2, 18
	v_mov_b32_e32 v224, 0xc0135761
	v_mov_b32_e32 v225, 1
	v_writelane_b32 v250, s3, 19
	s_add_u32 s2, s70, 0x5da0600
	s_addc_u32 s3, s71, 0
	v_writelane_b32 v250, s2, 20
	v_mov_b32_e32 v226, 0x3ecc95a3
	v_mov_b32_e32 v227, 0x3c088889
	v_writelane_b32 v250, s3, 21
	s_add_u32 s2, s70, 0x5da0700
	s_addc_u32 s3, s71, 0
	v_writelane_b32 v250, s2, 22
	v_mov_b32_e32 v228, 0x260
	v_mov_b64_e32 v[186:187], 0x440
	v_writelane_b32 v250, s3, 23
	s_add_u32 s2, s70, 0x5da0800
	s_addc_u32 s3, s71, 0
	v_writelane_b32 v250, s2, 24
	v_mov_b64_e32 v[188:189], 0x43f
	v_mov_b32_e32 v190, 0x3f317218
	v_writelane_b32 v250, s3, 25
	s_add_u32 s2, s70, 0x5da0900
	s_addc_u32 s3, s71, 0
	v_writelane_b32 v250, s2, 26
	v_mov_b32_e32 v229, 0x7f800000
	v_mov_b32_e32 v230, 0x7fc00000
	v_writelane_b32 v250, s3, 27
	s_add_u32 s2, s70, 0x5da0a00
	s_addc_u32 s3, s71, 0
	v_writelane_b32 v250, s2, 28
	v_mov_b32_e32 v231, 0xff800000
	v_mov_b64_e32 v[192:193], 0x21f
	v_writelane_b32 v250, s3, 29
	s_add_u32 s2, s70, 0x5da0b00
	s_addc_u32 s3, s71, 0
	v_writelane_b32 v250, s2, 30
	v_mov_b64_e32 v[194:195], 0xbb0
	v_mov_b64_e32 v[196:197], 0xbaf
	v_writelane_b32 v250, s3, 31
	s_add_u32 s2, s70, 0x5da0c00
	s_addc_u32 s3, s71, 0
	v_writelane_b32 v250, s2, 32
	v_mov_b64_e32 v[198:199], 0x1ff
	s_movk_i32 s92, 0x2000
	v_writelane_b32 v250, s3, 33
	s_add_u32 s2, s70, 0x5da0d00
	s_addc_u32 s3, s71, 0
	v_writelane_b32 v250, s2, 34
	s_mov_b32 s29, 0x800000
	s_movk_i32 s30, 0x80
	v_writelane_b32 v250, s3, 35
	s_add_u32 s2, s70, 0x5da0e00
	s_addc_u32 s3, s71, 0
	v_writelane_b32 v250, s2, 36
	s_mov_b32 s31, 0xbe99999a
	s_movk_i32 s34, 0x2c00
	v_writelane_b32 v250, s3, 37
	s_add_u32 s2, s70, 0x5da0f00
	s_addc_u32 s3, s71, 0
	v_writelane_b32 v250, s2, 38
	s_mov_b32 s93, 0
	s_mov_b64 s[96:97], 0x2000
	v_writelane_b32 v250, s3, 39
	s_add_u32 s2, s70, 0x5da1000
	s_addc_u32 s3, s71, 0
	v_writelane_b32 v250, s2, 40
	s_mov_b64 s[84:85], 0x8000
	s_nop 0
	v_writelane_b32 v250, s3, 41
	s_add_u32 s2, s70, 0x5da1100
	s_addc_u32 s3, s71, 0
	v_writelane_b32 v250, s2, 42
	s_nop 1
	v_writelane_b32 v250, s3, 43
	s_add_u32 s2, s70, 0x5da1200
	s_addc_u32 s3, s71, 0
	v_writelane_b32 v250, s2, 44
	s_nop 1
	v_writelane_b32 v250, s3, 45
	s_add_u32 s2, s70, 0x5da1300
	s_addc_u32 s3, s71, 0
	v_writelane_b32 v250, s2, 46
	s_cmp_eq_u32 s33, 15
	s_nop 0
	v_writelane_b32 v250, s3, 47
	s_cselect_b64 s[2:3], -1, 0
	v_writelane_b32 v250, s2, 48
	s_cmp_eq_u32 s33, 14
	s_nop 0
	v_writelane_b32 v250, s3, 49
	s_cselect_b64 s[2:3], -1, 0
	v_writelane_b32 v250, s2, 50
	s_cmp_eq_u32 s33, 13
	s_nop 0
	v_writelane_b32 v250, s3, 51
	s_cselect_b64 s[2:3], -1, 0
	v_writelane_b32 v250, s2, 52
	s_cmp_eq_u32 s33, 12
	s_nop 0
	v_writelane_b32 v250, s3, 53
	s_cselect_b64 s[2:3], -1, 0
	v_writelane_b32 v250, s2, 54
	s_cmp_eq_u32 s33, 11
	s_nop 0
	v_writelane_b32 v250, s3, 55
	s_cselect_b64 s[2:3], -1, 0
	v_writelane_b32 v250, s2, 56
	s_cmp_eq_u32 s33, 10
	s_nop 0
	v_writelane_b32 v250, s3, 57
	s_cselect_b64 s[2:3], -1, 0
	v_writelane_b32 v250, s2, 58
	s_cmp_eq_u32 s33, 9
	s_nop 0
	v_writelane_b32 v250, s3, 59
	s_cselect_b64 s[2:3], -1, 0
	v_writelane_b32 v250, s2, 60
	s_cmp_eq_u32 s33, 8
	s_nop 0
	v_writelane_b32 v250, s3, 61
	s_cselect_b64 s[2:3], -1, 0
	v_writelane_b32 v250, s2, 62
	s_cmp_eq_u32 s33, 7
	s_nop 0
	v_writelane_b32 v250, s3, 63
	s_cselect_b64 s[2:3], -1, 0
	v_writelane_b32 v249, s2, 0
	s_cmp_eq_u32 s33, 6
	s_nop 0
	v_writelane_b32 v249, s3, 1
	s_cselect_b64 s[2:3], -1, 0
	v_writelane_b32 v249, s2, 2
	s_cmp_eq_u32 s33, 5
	s_nop 0
	v_writelane_b32 v249, s3, 3
	s_cselect_b64 s[2:3], -1, 0
	v_writelane_b32 v249, s2, 4
	s_cmp_eq_u32 s33, 4
	s_nop 0
	v_writelane_b32 v249, s3, 5
	s_cselect_b64 s[2:3], -1, 0
	v_writelane_b32 v249, s2, 6
	s_cmp_eq_u32 s33, 3
	s_nop 0
	v_writelane_b32 v249, s3, 7
	s_cselect_b64 s[2:3], -1, 0
	v_writelane_b32 v249, s2, 8
	s_cmp_eq_u32 s33, 2
	s_nop 0
	v_writelane_b32 v249, s3, 9
	s_cselect_b64 s[2:3], -1, 0
	v_writelane_b32 v249, s2, 10
	s_cmp_eq_u32 s33, 1
	s_nop 0
	v_writelane_b32 v249, s3, 11
	s_cselect_b64 s[2:3], -1, 0
	v_writelane_b32 v249, s2, 12
	s_cmp_eq_u32 s33, 0
	s_nop 0
	v_writelane_b32 v249, s3, 13
	s_cselect_b64 s[2:3], -1, 0
	v_writelane_b32 v249, s2, 14
	s_nop 1
	v_writelane_b32 v249, s3, 15
	s_lshl_b32 s2, s33, 8
	s_add_u32 s0, s0, s2
	s_addc_u32 s1, s1, 0
	s_add_u32 s2, s0, 0x1400
	s_addc_u32 s3, s1, 0
	v_writelane_b32 v249, s2, 16
	s_add_u32 s0, s0, 0x2400
	s_addc_u32 s1, s1, 0
	v_writelane_b32 v249, s3, 17
	v_writelane_b32 v249, s0, 18
	s_nop 1
	v_writelane_b32 v249, s1, 19
	s_movk_i32 s0, 0x3ff
	v_and_or_b32 v0, v0, s0, v220
	s_add_u32 s0, s70, 0x5da3400
	s_addc_u32 s1, s71, 0
	v_writelane_b32 v249, s0, 20
	s_nop 1
	v_writelane_b32 v249, s1, 21
	s_add_u32 s0, s70, 0x5da3500
	s_addc_u32 s1, s71, 0
	v_writelane_b32 v249, s0, 22
	s_lshl_b32 s66, s74, 9
	v_cvt_f32_u32_e32 v1, s66
	v_writelane_b32 v249, s1, 23
	s_load_dwordx4 s[0:3], s[60:61], 0x0
	s_mov_b32 s67, s66
	v_rcp_iflag_f32_e32 v1, v1
	s_waitcnt lgkmcnt(0)
; __global__ void __launch_bounds__(NTHREADS, 2) mega(Args a) {
;     ...
;             { float* ssqH = (float*)(C.ws + WS_SSQH); for (int i = C.bid * NTHREADS + C.tid; i < M; i += C.G * NTHREADS) ssqH[i] = 0.f;
;               float* sab = (float*)(C.ws + WS_SSQ); for (int i = C.bid * NTHREADS + C.tid; i < 2 * M; i += C.G * NTHREADS) sab[i] = 0.f; }
;             for (int rep = 0; rep < REP_MIX; ++rep) {
;             ln_rows(C, l);
;             if ((C.G & 7) == 0) { LruHead H; load_lru_head(C, l, C.bid & 7, H);
;                 for (int it = C.bid; it < 128 * 8; it += C.G) lru_tile<1>(C, l, it >> 3, it & 7, H); }
;             else for (int it = C.bid; it < 128 * 8; it += C.G) { LruHead H; load_lru_head(C, l, it & 7, H); lru_tile<1>(C, l, it >> 3, it & 7, H); } }
	s_add_u32 s0, s2, 0xf8000000
	v_writelane_b32 v249, s0, 24
	s_addc_u32 s0, s3, -1
	v_writelane_b32 v249, s0, 25
	s_add_i32 s0, s74, 0x21f
	v_writelane_b32 v249, s0, 26
	s_lshl_b32 s0, s74, 1
	v_writelane_b32 v249, s0, 27
	s_add_i32 s0, s74, 0x1ff
	v_writelane_b32 v249, s0, 28
	s_and_b32 s0, s74, 7
	s_lshl_b32 s70, s74, 3
	v_mul_f32_e32 v1, 0x4f7ffffe, v1
	s_cmp_lg_u32 s0, 0
	v_cvt_u32_f32_e32 v1, v1
	s_cselect_b64 s[0:1], -1, 0
	v_writelane_b32 v249, s0, 29
	s_lshl_b32 s26, s74, 10
	s_ashr_i32 s71, s70, 31
	v_writelane_b32 v249, s1, 30
	s_sub_i32 s0, 0, s66
	v_mul_lo_u32 v2, s0, v1
	s_abs_i32 s0, s74
	v_cvt_f32_u32_e32 v3, s0
	v_writelane_b32 v249, s0, 31
	s_sub_i32 s0, 0, s0
	v_mul_hi_u32 v2, v1, v2
	v_rcp_iflag_f32_e32 v3, v3
	v_add_u32_e32 v222, v1, v2
	s_lshl_b64 s[90:91], s[70:71], 13
	v_mbcnt_lo_u32_b32 v2, -1, 0
	v_mul_f32_e32 v3, 0x4f7ffffe, v3
	v_cvt_u32_f32_e32 v3, v3
	v_mov_b32_e32 v1, 0
	v_mbcnt_hi_u32_b32 v221, -1, v2
	v_readfirstlane_b32 s1, v3
	s_mul_i32 s0, s0, s1
	s_mul_hi_u32 s0, s1, s0
	s_add_i32 s0, s1, s0
	v_writelane_b32 v249, s0, 32
	s_mov_b32 s1, -1
	s_mov_b32 s0, s39
	s_and_b64 s[0:1], s[66:67], s[0:1]
	v_writelane_b32 v249, s0, 33
	s_ashr_i32 s67, s66, 31
	s_lshl_b64 s[56:57], s[66:67], 2
	v_writelane_b32 v249, s1, 34
	s_mov_b32 s0, 1
	v_writelane_b32 v249, s0, 35
	v_writelane_b32 v249, s26, 36
	s_lshl_b32 s0, s74, 7
	v_writelane_b32 v249, s0, 37
	s_lshl_b32 s0, s74, 8
	v_writelane_b32 v249, s0, 38
	s_add_i32 s0, 0, 0x20000
	v_writelane_b32 v249, s0, 39
	s_add_i32 s0, 0, 0x20004
	v_writelane_b32 v249, s0, 40
	v_cmp_eq_u32_e64 s[0:1], 0, v0
	s_mov_b64 s[94:95], s[56:57]
	s_nop 0
	v_writelane_b32 v249, s0, 41
	s_nop 1
	v_writelane_b32 v249, s1, 42
	s_lshl_b64 s[0:1], s[70:71], 2
	v_writelane_b32 v249, s0, 43
	s_nop 1
	v_writelane_b32 v249, s1, 44
	s_lshl_b64 s[0:1], s[70:71], 12
	v_writelane_b32 v249, s0, 45
	v_readlane_b32 s71, v250, 0
	s_nop 0
	v_writelane_b32 v249, s1, 46
	s_mov_b64 s[0:1], -1
	v_writelane_b32 v249, s0, 47
	s_nop 1
	v_writelane_b32 v249, s1, 48
	s_mov_b64 s[0:1], 0x80
	v_writelane_b32 v249, s90, 49
	s_nop 1
	v_writelane_b32 v249, s91, 50
	s_branch .LBB0_106
	s_nop 0

; template <class Epi, class Sched, bool ALIGN_EPI = false, bool SP2 = false>
; __device__ __forceinline__ void gemm_phase(PG8_LAS unsigned char* lds, const Gemm g, const Sched& S, const Epi& E) {
;     ...
;         const bool has_next = S.next(ui + 1, nxt);
;         const char* nA = has_next ? (const char*)g.A + (size_t)nxt.pm * tstep + (size_t)nxt.kt0 * kstep : cA; const char* nB = has_next ? (const char*)g.Bt + (size_t)nxt.pn * tstep + (size_t)nxt.kt0 * kstep : cB;
;         const int nt = cur.nkt;
;         for (int t = 0; t < nt; t += 2) {
;             const bool last = (t == nt - 2);
;             const char* a1 = cA + (size_t)(t + 1) * kstep;
;             const char* a2 = last ? nA : cA + (size_t)(t + 2) * kstep; const char* b2 = last ? nB : cB + (size_t)(t + 2) * kstep;
;             const char* a3 = a2 + kstep; const char* b3 = b2 + kstep;
;             if (last && has_next) S.a_ready(nxt);
.LBB0_1400:
	s_ashr_i32 s63, s62, 31
	s_lshl_b64 s[2:3], s[62:63], 20
	s_add_u32 s45, s12, s2
	s_addc_u32 s63, s13, s3
	s_ashr_i32 s77, s76, 31
	s_lshl_b64 s[2:3], s[76:77], 7
	s_add_u32 s78, s45, s2
	s_addc_u32 s79, s63, s3
	s_and_b64 vcc, exec, s[42:43]
	s_mov_b64 s[80:81], s[22:23]
	s_cbranch_vccz .LBB0_1332
	s_branch .LBB0_1333
	s_nop 0
	s_nop 0
	s_nop 0
	s_nop 0
	s_nop 0
	s_nop 0
	s_nop 0
	s_nop 0
	s_nop 0
	s_nop 0
	s_nop 0
	s_nop 0
	s_nop 0
	s_nop 0
	s_nop 0
	s_nop 0
	s_nop 0
	s_nop 0
	s_nop 0
	s_nop 0
	s_nop 0
	s_nop 0
	s_nop 0
	s_nop 0
	s_nop 0
	s_nop 0
	s_nop 0
	s_nop 0
	s_nop 0
	s_nop 0
	s_nop 0
	s_nop 0
	s_nop 0
	s_nop 0
	s_nop 0
	s_nop 0
	s_nop 0
	s_nop 0
	s_nop 0
	s_nop 0
	s_nop 0
	s_nop 0
	s_nop 0
	s_nop 0
	s_nop 0
	s_nop 0
	s_nop 0
	s_nop 0
	s_nop 0
	s_nop 0
	s_nop 0
	s_nop 0
	s_nop 0
	s_nop 0
	s_nop 0
	s_nop 0
	s_nop 0
	s_nop 0
	s_nop 0
	s_nop 0
	s_nop 0
	s_nop 0
	s_nop 0
	s_nop 0
	s_nop 0
	s_nop 0
	s_nop 0
	s_nop 0
	s_nop 0
	s_nop 0
	s_nop 0
	s_nop 0
	s_nop 0
	s_nop 0
	s_nop 0
	s_nop 0
	s_nop 0
	s_nop 0
	s_nop 0
	s_nop 0
	s_nop 0
	s_nop 0
	s_nop 0
	s_nop 0
	s_nop 0
	s_nop 0
	s_nop 0
	s_nop 0
	s_nop 0
	s_nop 0
	s_nop 0
